# prep silu(cond) staging loads batched (18 in flight) + layer-0 out-proj epilogue pipelined 6 steps deep
# speedup vs baseline: 1.0582x; 1.0022x over previous
.LBB0_39:
	s_movk_i32 s0, 0x2400
	v_cmp_gt_i32_e32 vcc, s0, v200
	s_and_saveexec_b64 s[2:3], vcc
	s_cbranch_execz .LBB0_46
	s_load_dwordx2 s[0:1], s[76:77], 0x20
	s_load_dwordx2 s[6:7], s[76:77], 0x28
	s_add_i32 s14, s90, 0
	s_waitcnt vmcnt(0)
	v_lshl_add_u32 v4, v200, 2, s14
	v_lshlrev_b32_e32 v0, 2, v200
	s_waitcnt lgkmcnt(0)
	global_load_dword v60, v0, s[6:7]
	global_load_dword v61, v0, s[6:7] offset:2048
	global_load_dword v62, v0, s[0:1]
	global_load_dword v63, v0, s[0:1] offset:2048
	s_add_u32 s0, s0, 0x1000
	s_addc_u32 s1, s1, 0
	global_load_dword v64, v0, s[0:1]
	global_load_dword v65, v0, s[0:1] offset:2048
	s_add_u32 s0, s0, 0x1000
	s_addc_u32 s1, s1, 0
	global_load_dword v66, v0, s[0:1]
	global_load_dword v67, v0, s[0:1] offset:2048
	s_add_u32 s0, s0, 0x1000
	s_addc_u32 s1, s1, 0
	global_load_dword v68, v0, s[0:1]
	global_load_dword v69, v0, s[0:1] offset:2048
	s_add_u32 s0, s0, 0x1000
	s_addc_u32 s1, s1, 0
	global_load_dword v70, v0, s[0:1]
	global_load_dword v71, v0, s[0:1] offset:2048
	s_add_u32 s0, s0, 0x1000
	s_addc_u32 s1, s1, 0
	global_load_dword v72, v0, s[0:1]
	global_load_dword v73, v0, s[0:1] offset:2048
	s_add_u32 s0, s0, 0x1000
	s_addc_u32 s1, s1, 0
	global_load_dword v74, v0, s[0:1]
	global_load_dword v75, v0, s[0:1] offset:2048
	s_add_u32 s0, s0, 0x1000
	s_addc_u32 s1, s1, 0
	global_load_dword v76, v0, s[0:1]
	global_load_dword v77, v0, s[0:1] offset:2048
	s_waitcnt vmcnt(17)
	v_mul_f32_e32 v2, 0xbfb8aa3b, v60
	v_exp_f32_e32 v2, v2
	s_nop 0
	v_add_f32_e32 v2, 1.0, v2
	v_div_scale_f32 v5, s[0:1], v2, v2, v60
	v_rcp_f32_e32 v6, v5
	v_div_scale_f32 v7, vcc, v60, v2, v60
	v_fma_f32 v8, -v5, v6, 1.0
	v_fmac_f32_e32 v6, v8, v6
	v_mul_f32_e32 v8, v7, v6
	v_fma_f32 v9, -v5, v8, v7
	v_fmac_f32_e32 v8, v9, v6
	v_fma_f32 v5, -v5, v8, v7
	v_div_fmas_f32 v5, v5, v6, v8
	v_div_fixup_f32 v3, v5, v2, v60
	ds_write_b32 v4, v3
	s_waitcnt vmcnt(16)
	v_mul_f32_e32 v2, 0xbfb8aa3b, v61
	v_exp_f32_e32 v2, v2
	s_nop 0
	v_add_f32_e32 v2, 1.0, v2
	v_div_scale_f32 v5, s[0:1], v2, v2, v61
	v_rcp_f32_e32 v6, v5
	v_div_scale_f32 v7, vcc, v61, v2, v61
	v_fma_f32 v8, -v5, v6, 1.0
	v_fmac_f32_e32 v6, v8, v6
	v_mul_f32_e32 v8, v7, v6
	v_fma_f32 v9, -v5, v8, v7
	v_fmac_f32_e32 v8, v9, v6
	v_fma_f32 v5, -v5, v8, v7
	v_div_fmas_f32 v5, v5, v6, v8
	v_div_fixup_f32 v3, v5, v2, v61
	ds_write_b32 v4, v3 offset:2048
	s_waitcnt vmcnt(15)
	v_mul_f32_e32 v2, 0xbfb8aa3b, v62
	v_exp_f32_e32 v2, v2
	s_nop 0
	v_add_f32_e32 v2, 1.0, v2
	v_div_scale_f32 v5, s[0:1], v2, v2, v62
	v_rcp_f32_e32 v6, v5
	v_div_scale_f32 v7, vcc, v62, v2, v62
	v_fma_f32 v8, -v5, v6, 1.0
	v_fmac_f32_e32 v6, v8, v6
	v_mul_f32_e32 v8, v7, v6
	v_fma_f32 v9, -v5, v8, v7
	v_fmac_f32_e32 v8, v9, v6
	v_fma_f32 v5, -v5, v8, v7
	v_div_fmas_f32 v5, v5, v6, v8
	v_div_fixup_f32 v3, v5, v2, v62
	ds_write_b32 v4, v3 offset:4096
	s_waitcnt vmcnt(14)
	v_mul_f32_e32 v2, 0xbfb8aa3b, v63
	v_exp_f32_e32 v2, v2
	s_nop 0
	v_add_f32_e32 v2, 1.0, v2
	v_div_scale_f32 v5, s[0:1], v2, v2, v63
	v_rcp_f32_e32 v6, v5
	v_div_scale_f32 v7, vcc, v63, v2, v63
	v_fma_f32 v8, -v5, v6, 1.0
	v_fmac_f32_e32 v6, v8, v6
	v_mul_f32_e32 v8, v7, v6
	v_fma_f32 v9, -v5, v8, v7
	v_fmac_f32_e32 v8, v9, v6
	v_fma_f32 v5, -v5, v8, v7
	v_div_fmas_f32 v5, v5, v6, v8
	v_div_fixup_f32 v3, v5, v2, v63
	ds_write_b32 v4, v3 offset:6144
	s_waitcnt vmcnt(13)
	v_mul_f32_e32 v2, 0xbfb8aa3b, v64
	v_exp_f32_e32 v2, v2
	s_nop 0
	v_add_f32_e32 v2, 1.0, v2
	v_div_scale_f32 v5, s[0:1], v2, v2, v64
	v_rcp_f32_e32 v6, v5
	v_div_scale_f32 v7, vcc, v64, v2, v64
	v_fma_f32 v8, -v5, v6, 1.0
	v_fmac_f32_e32 v6, v8, v6
	v_mul_f32_e32 v8, v7, v6
	v_fma_f32 v9, -v5, v8, v7
	v_fmac_f32_e32 v8, v9, v6
	v_fma_f32 v5, -v5, v8, v7
	v_div_fmas_f32 v5, v5, v6, v8
	v_div_fixup_f32 v3, v5, v2, v64
	ds_write_b32 v4, v3 offset:8192
	s_waitcnt vmcnt(12)
	v_mul_f32_e32 v2, 0xbfb8aa3b, v65
	v_exp_f32_e32 v2, v2
	s_nop 0
	v_add_f32_e32 v2, 1.0, v2
	v_div_scale_f32 v5, s[0:1], v2, v2, v65
	v_rcp_f32_e32 v6, v5
	v_div_scale_f32 v7, vcc, v65, v2, v65
	v_fma_f32 v8, -v5, v6, 1.0
	v_fmac_f32_e32 v6, v8, v6
	v_mul_f32_e32 v8, v7, v6
	v_fma_f32 v9, -v5, v8, v7
	v_fmac_f32_e32 v8, v9, v6
	v_fma_f32 v5, -v5, v8, v7
	v_div_fmas_f32 v5, v5, v6, v8
	v_div_fixup_f32 v3, v5, v2, v65
	ds_write_b32 v4, v3 offset:10240
	s_waitcnt vmcnt(11)
	v_mul_f32_e32 v2, 0xbfb8aa3b, v66
	v_exp_f32_e32 v2, v2
	s_nop 0
	v_add_f32_e32 v2, 1.0, v2
	v_div_scale_f32 v5, s[0:1], v2, v2, v66
	v_rcp_f32_e32 v6, v5
	v_div_scale_f32 v7, vcc, v66, v2, v66
	v_fma_f32 v8, -v5, v6, 1.0
	v_fmac_f32_e32 v6, v8, v6
	v_mul_f32_e32 v8, v7, v6
	v_fma_f32 v9, -v5, v8, v7
	v_fmac_f32_e32 v8, v9, v6
	v_fma_f32 v5, -v5, v8, v7
	v_div_fmas_f32 v5, v5, v6, v8
	v_div_fixup_f32 v3, v5, v2, v66
	ds_write_b32 v4, v3 offset:12288
	s_waitcnt vmcnt(10)
	v_mul_f32_e32 v2, 0xbfb8aa3b, v67
	v_exp_f32_e32 v2, v2
	s_nop 0
	v_add_f32_e32 v2, 1.0, v2
	v_div_scale_f32 v5, s[0:1], v2, v2, v67
	v_rcp_f32_e32 v6, v5
	v_div_scale_f32 v7, vcc, v67, v2, v67
	v_fma_f32 v8, -v5, v6, 1.0
	v_fmac_f32_e32 v6, v8, v6
	v_mul_f32_e32 v8, v7, v6
	v_fma_f32 v9, -v5, v8, v7
	v_fmac_f32_e32 v8, v9, v6
	v_fma_f32 v5, -v5, v8, v7
	v_div_fmas_f32 v5, v5, v6, v8
	v_div_fixup_f32 v3, v5, v2, v67
	ds_write_b32 v4, v3 offset:14336
	s_waitcnt vmcnt(9)
	v_mul_f32_e32 v2, 0xbfb8aa3b, v68
	v_exp_f32_e32 v2, v2
	s_nop 0
	v_add_f32_e32 v2, 1.0, v2
	v_div_scale_f32 v5, s[0:1], v2, v2, v68
	v_rcp_f32_e32 v6, v5
	v_div_scale_f32 v7, vcc, v68, v2, v68
	v_fma_f32 v8, -v5, v6, 1.0
	v_fmac_f32_e32 v6, v8, v6
	v_mul_f32_e32 v8, v7, v6
	v_fma_f32 v9, -v5, v8, v7
	v_fmac_f32_e32 v8, v9, v6
	v_fma_f32 v5, -v5, v8, v7
	v_div_fmas_f32 v5, v5, v6, v8
	v_div_fixup_f32 v3, v5, v2, v68
	ds_write_b32 v4, v3 offset:16384
	s_waitcnt vmcnt(8)
	v_mul_f32_e32 v2, 0xbfb8aa3b, v69
	v_exp_f32_e32 v2, v2
	s_nop 0
	v_add_f32_e32 v2, 1.0, v2
	v_div_scale_f32 v5, s[0:1], v2, v2, v69
	v_rcp_f32_e32 v6, v5
	v_div_scale_f32 v7, vcc, v69, v2, v69
	v_fma_f32 v8, -v5, v6, 1.0
	v_fmac_f32_e32 v6, v8, v6
	v_mul_f32_e32 v8, v7, v6
	v_fma_f32 v9, -v5, v8, v7
	v_fmac_f32_e32 v8, v9, v6
	v_fma_f32 v5, -v5, v8, v7
	v_div_fmas_f32 v5, v5, v6, v8
	v_div_fixup_f32 v3, v5, v2, v69
	ds_write_b32 v4, v3 offset:18432
	s_waitcnt vmcnt(7)
	v_mul_f32_e32 v2, 0xbfb8aa3b, v70
	v_exp_f32_e32 v2, v2
	s_nop 0
	v_add_f32_e32 v2, 1.0, v2
	v_div_scale_f32 v5, s[0:1], v2, v2, v70
	v_rcp_f32_e32 v6, v5
	v_div_scale_f32 v7, vcc, v70, v2, v70
	v_fma_f32 v8, -v5, v6, 1.0
	v_fmac_f32_e32 v6, v8, v6
	v_mul_f32_e32 v8, v7, v6
	v_fma_f32 v9, -v5, v8, v7
	v_fmac_f32_e32 v8, v9, v6
	v_fma_f32 v5, -v5, v8, v7
	v_div_fmas_f32 v5, v5, v6, v8
	v_div_fixup_f32 v3, v5, v2, v70
	ds_write_b32 v4, v3 offset:20480
	s_waitcnt vmcnt(6)
	v_mul_f32_e32 v2, 0xbfb8aa3b, v71
	v_exp_f32_e32 v2, v2
	s_nop 0
	v_add_f32_e32 v2, 1.0, v2
	v_div_scale_f32 v5, s[0:1], v2, v2, v71
	v_rcp_f32_e32 v6, v5
	v_div_scale_f32 v7, vcc, v71, v2, v71
	v_fma_f32 v8, -v5, v6, 1.0
	v_fmac_f32_e32 v6, v8, v6
	v_mul_f32_e32 v8, v7, v6
	v_fma_f32 v9, -v5, v8, v7
	v_fmac_f32_e32 v8, v9, v6
	v_fma_f32 v5, -v5, v8, v7
	v_div_fmas_f32 v5, v5, v6, v8
	v_div_fixup_f32 v3, v5, v2, v71
	ds_write_b32 v4, v3 offset:22528
	s_waitcnt vmcnt(5)
	v_mul_f32_e32 v2, 0xbfb8aa3b, v72
	v_exp_f32_e32 v2, v2
	s_nop 0
	v_add_f32_e32 v2, 1.0, v2
	v_div_scale_f32 v5, s[0:1], v2, v2, v72
	v_rcp_f32_e32 v6, v5
	v_div_scale_f32 v7, vcc, v72, v2, v72
	v_fma_f32 v8, -v5, v6, 1.0
	v_fmac_f32_e32 v6, v8, v6
	v_mul_f32_e32 v8, v7, v6
	v_fma_f32 v9, -v5, v8, v7
	v_fmac_f32_e32 v8, v9, v6
	v_fma_f32 v5, -v5, v8, v7
	v_div_fmas_f32 v5, v5, v6, v8
	v_div_fixup_f32 v3, v5, v2, v72
	ds_write_b32 v4, v3 offset:24576
	s_waitcnt vmcnt(4)
	v_mul_f32_e32 v2, 0xbfb8aa3b, v73
	v_exp_f32_e32 v2, v2
	s_nop 0
	v_add_f32_e32 v2, 1.0, v2
	v_div_scale_f32 v5, s[0:1], v2, v2, v73
	v_rcp_f32_e32 v6, v5
	v_div_scale_f32 v7, vcc, v73, v2, v73
	v_fma_f32 v8, -v5, v6, 1.0
	v_fmac_f32_e32 v6, v8, v6
	v_mul_f32_e32 v8, v7, v6
	v_fma_f32 v9, -v5, v8, v7
	v_fmac_f32_e32 v8, v9, v6
	v_fma_f32 v5, -v5, v8, v7
	v_div_fmas_f32 v5, v5, v6, v8
	v_div_fixup_f32 v3, v5, v2, v73
	ds_write_b32 v4, v3 offset:26624
	s_waitcnt vmcnt(3)
	v_mul_f32_e32 v2, 0xbfb8aa3b, v74
	v_exp_f32_e32 v2, v2
	s_nop 0
	v_add_f32_e32 v2, 1.0, v2
	v_div_scale_f32 v5, s[0:1], v2, v2, v74
	v_rcp_f32_e32 v6, v5
	v_div_scale_f32 v7, vcc, v74, v2, v74
	v_fma_f32 v8, -v5, v6, 1.0
	v_fmac_f32_e32 v6, v8, v6
	v_mul_f32_e32 v8, v7, v6
	v_fma_f32 v9, -v5, v8, v7
	v_fmac_f32_e32 v8, v9, v6
	v_fma_f32 v5, -v5, v8, v7
	v_div_fmas_f32 v5, v5, v6, v8
	v_div_fixup_f32 v3, v5, v2, v74
	ds_write_b32 v4, v3 offset:28672
	s_waitcnt vmcnt(2)
	v_mul_f32_e32 v2, 0xbfb8aa3b, v75
	v_exp_f32_e32 v2, v2
	s_nop 0
	v_add_f32_e32 v2, 1.0, v2
	v_div_scale_f32 v5, s[0:1], v2, v2, v75
	v_rcp_f32_e32 v6, v5
	v_div_scale_f32 v7, vcc, v75, v2, v75
	v_fma_f32 v8, -v5, v6, 1.0
	v_fmac_f32_e32 v6, v8, v6
	v_mul_f32_e32 v8, v7, v6
	v_fma_f32 v9, -v5, v8, v7
	v_fmac_f32_e32 v8, v9, v6
	v_fma_f32 v5, -v5, v8, v7
	v_div_fmas_f32 v5, v5, v6, v8
	v_div_fixup_f32 v3, v5, v2, v75
	ds_write_b32 v4, v3 offset:30720
	s_waitcnt vmcnt(1)
	v_mul_f32_e32 v2, 0xbfb8aa3b, v76
	v_exp_f32_e32 v2, v2
	s_nop 0
	v_add_f32_e32 v2, 1.0, v2
	v_div_scale_f32 v5, s[0:1], v2, v2, v76
	v_rcp_f32_e32 v6, v5
	v_div_scale_f32 v7, vcc, v76, v2, v76
	v_fma_f32 v8, -v5, v6, 1.0
	v_fmac_f32_e32 v6, v8, v6
	v_mul_f32_e32 v8, v7, v6
	v_fma_f32 v9, -v5, v8, v7
	v_fmac_f32_e32 v8, v9, v6
	v_fma_f32 v5, -v5, v8, v7
	v_div_fmas_f32 v5, v5, v6, v8
	v_div_fixup_f32 v3, v5, v2, v76
	ds_write_b32 v4, v3 offset:32768
	s_waitcnt vmcnt(0)
	v_mul_f32_e32 v2, 0xbfb8aa3b, v77
	v_exp_f32_e32 v2, v2
	s_nop 0
	v_add_f32_e32 v2, 1.0, v2
	v_div_scale_f32 v5, s[0:1], v2, v2, v77
	v_rcp_f32_e32 v6, v5
	v_div_scale_f32 v7, vcc, v77, v2, v77
	v_fma_f32 v8, -v5, v6, 1.0
	v_fmac_f32_e32 v6, v8, v6
	v_mul_f32_e32 v8, v7, v6
	v_fma_f32 v9, -v5, v8, v7
	v_fmac_f32_e32 v8, v9, v6
	v_fma_f32 v5, -v5, v8, v7
	v_div_fmas_f32 v5, v5, v6, v8
	v_div_fixup_f32 v3, v5, v2, v77
	ds_write_b32 v4, v3 offset:34816

.LBB0_794:
	v_add_u32_e32 v0, s10, v161
	ds_read_b128 v[122:125], v0
	ds_read_b128 v[126:129], v0 offset:1024
	ds_read_b128 v[130:133], v0 offset:2048
	ds_read_b128 v[134:137], v0 offset:3072
	s_add_u32 s0, s20, 0xfffc0080
	s_addc_u32 s1, s21, -1
	s_cmp_eq_u32 s71, 12
	s_cselect_b32 s49, s7, s1
	s_cselect_b32 s48, s67, s0
	s_cselect_b32 s35, s3, s70
	s_cselect_b32 s34, s68, s69
	v_lshl_add_u64 v[158:159], s[20:21], 0, v[150:151]
	s_add_i32 m0, s24, 0xc000
	ds_read_b128 v[154:157], v163
	ds_read_b128 v[164:167], v163 offset:1024
	ds_read_b128 v[168:171], v163 offset:2048
	ds_read_b128 v[172:175], v163 offset:3072
	ds_read_b128 v[176:179], v163 offset:4096
	ds_read_b128 v[180:183], v163 offset:5120
	ds_read_b128 v[184:187], v163 offset:6144
	ds_read_b128 v[202:205], v163 offset:7168
	global_load_lds_dwordx4 v[158:159], off
	v_lshl_add_u64 v[158:159], s[20:21], 0, v[152:153]
	s_add_i32 m0, s24, 0xe000
	s_nop 0
	global_load_lds_dwordx4 v[158:159], off
	s_waitcnt lgkmcnt(8)
	s_barrier
	s_waitcnt lgkmcnt(0)
	s_setprio 1
	s_waitcnt lgkmcnt(0)
	v_mfma_f32_16x16x32_bf16 v[142:145], v[122:125], v[154:157], v[142:145]
	v_mfma_f32_16x16x32_bf16 v[138:141], v[130:133], v[154:157], v[138:141]
	v_mfma_f32_16x16x32_bf16 v[110:113], v[122:125], v[168:171], v[110:113]
	v_mfma_f32_16x16x32_bf16 v[106:109], v[130:133], v[168:171], v[106:109]
	v_mfma_f32_16x16x32_bf16 v[94:97], v[122:125], v[176:179], v[94:97]
	v_mfma_f32_16x16x32_bf16 v[90:93], v[130:133], v[176:179], v[90:93]
	v_mfma_f32_16x16x32_bf16 v[78:81], v[122:125], v[184:187], v[78:81]
	v_mfma_f32_16x16x32_bf16 v[74:77], v[130:133], v[184:187], v[74:77]
	v_mfma_f32_16x16x32_bf16 v[142:145], v[126:129], v[164:167], v[142:145]
	v_mfma_f32_16x16x32_bf16 v[138:141], v[134:137], v[164:167], v[138:141]
	v_mfma_f32_16x16x32_bf16 v[110:113], v[126:129], v[172:175], v[110:113]
	v_mfma_f32_16x16x32_bf16 v[106:109], v[134:137], v[172:175], v[106:109]
	v_mfma_f32_16x16x32_bf16 v[94:97], v[126:129], v[180:183], v[94:97]
	v_mfma_f32_16x16x32_bf16 v[90:93], v[134:137], v[180:183], v[90:93]
	v_mfma_f32_16x16x32_bf16 v[78:81], v[126:129], v[202:205], v[78:81]
	v_mfma_f32_16x16x32_bf16 v[74:77], v[134:137], v[202:205], v[74:77]
	s_setprio 0
	s_barrier
	s_mov_b32 m0, s11
	v_add_u32_e32 v0, s26, v161
	v_lshl_add_u64 v[158:159], s[34:35], 0, v[148:149]
	ds_read_b128 v[206:209], v0
	ds_read_b128 v[210:213], v0 offset:1024
	ds_read_b128 v[214:217], v0 offset:2048
	ds_read_b128 v[218:221], v0 offset:3072
	global_load_lds_dwordx4 v[158:159], off
	v_lshl_add_u64 v[188:189], s[34:35], 0, v[146:147]
	s_mov_b32 m0, s19
	s_nop 0
	global_load_lds_dwordx4 v[188:189], off
	s_barrier
	s_waitcnt lgkmcnt(0)
	s_setprio 1
	s_waitcnt lgkmcnt(0)
	v_mfma_f32_16x16x32_bf16 v[118:121], v[206:209], v[154:157], v[118:121]
	v_mfma_f32_16x16x32_bf16 v[114:117], v[214:217], v[154:157], v[114:117]
	v_mfma_f32_16x16x32_bf16 v[102:105], v[206:209], v[168:171], v[102:105]
	v_mfma_f32_16x16x32_bf16 v[98:101], v[214:217], v[168:171], v[98:101]
	v_mfma_f32_16x16x32_bf16 v[86:89], v[206:209], v[176:179], v[86:89]
	v_mfma_f32_16x16x32_bf16 v[82:85], v[214:217], v[176:179], v[82:85]
	v_mfma_f32_16x16x32_bf16 v[70:73], v[206:209], v[184:187], v[70:73]
	v_mfma_f32_16x16x32_bf16 v[66:69], v[214:217], v[184:187], v[66:69]
	v_mfma_f32_16x16x32_bf16 v[118:121], v[210:213], v[164:167], v[118:121]
	v_mfma_f32_16x16x32_bf16 v[114:117], v[218:221], v[164:167], v[114:117]
	v_mfma_f32_16x16x32_bf16 v[102:105], v[210:213], v[172:175], v[102:105]
	v_mfma_f32_16x16x32_bf16 v[98:101], v[218:221], v[172:175], v[98:101]
	v_mfma_f32_16x16x32_bf16 v[86:89], v[210:213], v[180:183], v[86:89]
	v_mfma_f32_16x16x32_bf16 v[82:85], v[218:221], v[180:183], v[82:85]
	v_mfma_f32_16x16x32_bf16 v[70:73], v[210:213], v[202:205], v[70:73]
	v_mfma_f32_16x16x32_bf16 v[66:69], v[218:221], v[202:205], v[66:69]
	s_setprio 0
	s_mov_b32 m0, s24
	v_lshl_add_u64 v[194:195], s[48:49], 0, v[148:149]
	s_barrier
	ds_read_b128 v[154:157], v163 offset:16384
	ds_read_b128 v[164:167], v163 offset:17408
	ds_read_b128 v[168:171], v163 offset:18432
	ds_read_b128 v[172:175], v163 offset:19456
	ds_read_b128 v[176:179], v163 offset:20480
	ds_read_b128 v[180:183], v163 offset:21504
	ds_read_b128 v[184:187], v163 offset:22528
	ds_read_b128 v[202:205], v163 offset:23552
	global_load_lds_dwordx4 v[194:195], off
	v_lshl_add_u64 v[196:197], s[48:49], 0, v[146:147]
	s_mov_b32 m0, s25
	s_nop 0
	global_load_lds_dwordx4 v[196:197], off
	s_barrier
	s_waitcnt lgkmcnt(0)
	s_setprio 1
	s_waitcnt lgkmcnt(0)
	v_mfma_f32_16x16x32_bf16 v[62:65], v[122:125], v[154:157], v[62:65]
	v_mfma_f32_16x16x32_bf16 v[58:61], v[130:133], v[154:157], v[58:61]
	v_mfma_f32_16x16x32_bf16 v[46:49], v[122:125], v[168:171], v[46:49]
	v_mfma_f32_16x16x32_bf16 v[42:45], v[130:133], v[168:171], v[42:45]
	v_mfma_f32_16x16x32_bf16 v[30:33], v[122:125], v[176:179], v[30:33]
	v_mfma_f32_16x16x32_bf16 v[26:29], v[130:133], v[176:179], v[26:29]
	v_mfma_f32_16x16x32_bf16 v[14:17], v[122:125], v[184:187], v[14:17]
	v_mfma_f32_16x16x32_bf16 v[10:13], v[130:133], v[184:187], v[10:13]
	v_mfma_f32_16x16x32_bf16 v[62:65], v[126:129], v[164:167], v[62:65]
	v_mfma_f32_16x16x32_bf16 v[58:61], v[134:137], v[164:167], v[58:61]
	v_mfma_f32_16x16x32_bf16 v[46:49], v[126:129], v[172:175], v[46:49]
	v_mfma_f32_16x16x32_bf16 v[42:45], v[134:137], v[172:175], v[42:45]
	v_mfma_f32_16x16x32_bf16 v[30:33], v[126:129], v[180:183], v[30:33]
	v_mfma_f32_16x16x32_bf16 v[26:29], v[134:137], v[180:183], v[26:29]
	v_mfma_f32_16x16x32_bf16 v[14:17], v[126:129], v[202:205], v[14:17]
	v_mfma_f32_16x16x32_bf16 v[10:13], v[134:137], v[202:205], v[10:13]
	s_setprio 0
	s_barrier
	s_add_u32 s0, s34, 0x40000
	s_addc_u32 s1, s35, 0
	s_mov_b32 m0, s28
	v_lshl_add_u64 v[122:123], s[0:1], 0, v[148:149]
	global_load_lds_dwordx4 v[122:123], off
	v_lshl_add_u64 v[122:123], s[0:1], 0, v[146:147]
	s_mov_b32 m0, s29
	s_nop 0
	global_load_lds_dwordx4 v[122:123], off
	s_waitcnt vmcnt(6)
	s_barrier
	s_setprio 1
	v_mfma_f32_16x16x32_bf16 v[54:57], v[206:209], v[154:157], v[54:57]
	v_mfma_f32_16x16x32_bf16 v[50:53], v[214:217], v[154:157], v[50:53]
	v_mfma_f32_16x16x32_bf16 v[38:41], v[206:209], v[168:171], v[38:41]
	v_mfma_f32_16x16x32_bf16 v[34:37], v[214:217], v[168:171], v[34:37]
	v_mfma_f32_16x16x32_bf16 v[22:25], v[206:209], v[176:179], v[22:25]
	v_mfma_f32_16x16x32_bf16 v[18:21], v[214:217], v[176:179], v[18:21]
	v_mfma_f32_16x16x32_bf16 v[6:9], v[206:209], v[184:187], v[6:9]
	v_mfma_f32_16x16x32_bf16 v[2:5], v[214:217], v[184:187], v[2:5]
	v_mfma_f32_16x16x32_bf16 v[54:57], v[210:213], v[164:167], v[54:57]
	v_mfma_f32_16x16x32_bf16 v[50:53], v[218:221], v[164:167], v[50:53]
	v_mfma_f32_16x16x32_bf16 v[38:41], v[210:213], v[172:175], v[38:41]
	v_mfma_f32_16x16x32_bf16 v[34:37], v[218:221], v[172:175], v[34:37]
	v_mfma_f32_16x16x32_bf16 v[22:25], v[210:213], v[180:183], v[22:25]
	v_mfma_f32_16x16x32_bf16 v[18:21], v[218:221], v[180:183], v[18:21]
	v_mfma_f32_16x16x32_bf16 v[6:9], v[210:213], v[202:205], v[6:9]
	v_mfma_f32_16x16x32_bf16 v[2:5], v[218:221], v[202:205], v[2:5]
	s_setprio 0
	v_add_u32_e32 v0, s43, v161
	s_barrier
	ds_read_b128 v[122:125], v0
	ds_read_b128 v[126:129], v0 offset:1024
	ds_read_b128 v[130:133], v0 offset:2048
	ds_read_b128 v[134:137], v0 offset:3072
	s_add_u32 s0, s48, 0x40000
	s_addc_u32 s1, s49, 0
	s_mov_b32 m0, s30
	v_lshl_add_u64 v[206:207], s[0:1], 0, v[148:149]
	ds_read_b128 v[154:157], v163 offset:32768
	ds_read_b128 v[164:167], v163 offset:33792
	ds_read_b128 v[168:171], v163 offset:34816
	ds_read_b128 v[172:175], v163 offset:35840
	ds_read_b128 v[176:179], v163 offset:36864
	ds_read_b128 v[180:183], v163 offset:37888
	ds_read_b128 v[184:187], v163 offset:38912
	ds_read_b128 v[202:205], v163 offset:39936
	global_load_lds_dwordx4 v[206:207], off
	v_lshl_add_u64 v[206:207], s[0:1], 0, v[146:147]
	s_mov_b32 m0, s36
	s_nop 0
	global_load_lds_dwordx4 v[206:207], off
	s_waitcnt lgkmcnt(8)
	s_barrier
	s_waitcnt lgkmcnt(0)
	s_setprio 1
	s_waitcnt lgkmcnt(0)
	v_mfma_f32_16x16x32_bf16 v[142:145], v[122:125], v[154:157], v[142:145]
	v_mfma_f32_16x16x32_bf16 v[138:141], v[130:133], v[154:157], v[138:141]
	v_mfma_f32_16x16x32_bf16 v[110:113], v[122:125], v[168:171], v[110:113]
	v_mfma_f32_16x16x32_bf16 v[106:109], v[130:133], v[168:171], v[106:109]
	v_mfma_f32_16x16x32_bf16 v[94:97], v[122:125], v[176:179], v[94:97]
	v_mfma_f32_16x16x32_bf16 v[90:93], v[130:133], v[176:179], v[90:93]
	v_mfma_f32_16x16x32_bf16 v[78:81], v[122:125], v[184:187], v[78:81]
	v_mfma_f32_16x16x32_bf16 v[74:77], v[130:133], v[184:187], v[74:77]
	v_mfma_f32_16x16x32_bf16 v[142:145], v[126:129], v[164:167], v[142:145]
	v_mfma_f32_16x16x32_bf16 v[138:141], v[134:137], v[164:167], v[138:141]
	v_mfma_f32_16x16x32_bf16 v[110:113], v[126:129], v[172:175], v[110:113]
	v_mfma_f32_16x16x32_bf16 v[106:109], v[134:137], v[172:175], v[106:109]
	v_mfma_f32_16x16x32_bf16 v[94:97], v[126:129], v[180:183], v[94:97]
	v_mfma_f32_16x16x32_bf16 v[90:93], v[134:137], v[180:183], v[90:93]
	v_mfma_f32_16x16x32_bf16 v[78:81], v[126:129], v[202:205], v[78:81]
	v_mfma_f32_16x16x32_bf16 v[74:77], v[134:137], v[202:205], v[74:77]
	s_setprio 0
	s_barrier
	s_mov_b32 m0, s50
	v_add_u32_e32 v0, s58, v161
	v_lshl_add_u64 v[158:159], v[158:159], 0, s[88:89]
	ds_read_b128 v[206:209], v0
	ds_read_b128 v[210:213], v0 offset:1024
	ds_read_b128 v[214:217], v0 offset:2048
	ds_read_b128 v[218:221], v0 offset:3072
	global_load_lds_dwordx4 v[158:159], off
	v_lshl_add_u64 v[158:159], v[188:189], 0, s[88:89]
	s_mov_b32 m0, s51
	s_nop 0
	global_load_lds_dwordx4 v[158:159], off
	s_barrier
	s_waitcnt lgkmcnt(0)
	s_setprio 1
	s_waitcnt lgkmcnt(0)
	v_mfma_f32_16x16x32_bf16 v[118:121], v[206:209], v[154:157], v[118:121]
	v_mfma_f32_16x16x32_bf16 v[114:117], v[214:217], v[154:157], v[114:117]
	v_mfma_f32_16x16x32_bf16 v[102:105], v[206:209], v[168:171], v[102:105]
	v_mfma_f32_16x16x32_bf16 v[98:101], v[214:217], v[168:171], v[98:101]
	v_mfma_f32_16x16x32_bf16 v[86:89], v[206:209], v[176:179], v[86:89]
	v_mfma_f32_16x16x32_bf16 v[82:85], v[214:217], v[176:179], v[82:85]
	v_mfma_f32_16x16x32_bf16 v[70:73], v[206:209], v[184:187], v[70:73]
	v_mfma_f32_16x16x32_bf16 v[66:69], v[214:217], v[184:187], v[66:69]
	v_mfma_f32_16x16x32_bf16 v[118:121], v[210:213], v[164:167], v[118:121]
	v_mfma_f32_16x16x32_bf16 v[114:117], v[218:221], v[164:167], v[114:117]
	v_mfma_f32_16x16x32_bf16 v[102:105], v[210:213], v[172:175], v[102:105]
	v_mfma_f32_16x16x32_bf16 v[98:101], v[218:221], v[172:175], v[98:101]
	v_mfma_f32_16x16x32_bf16 v[86:89], v[210:213], v[180:183], v[86:89]
	v_mfma_f32_16x16x32_bf16 v[82:85], v[218:221], v[180:183], v[82:85]
	v_mfma_f32_16x16x32_bf16 v[70:73], v[210:213], v[202:205], v[70:73]
	v_mfma_f32_16x16x32_bf16 v[66:69], v[218:221], v[202:205], v[66:69]
	s_setprio 0
	s_mov_b32 m0, s54
	v_lshl_add_u64 v[158:159], v[194:195], 0, s[88:89]
	s_barrier
	ds_read_b128 v[154:157], v163 offset:49152
	ds_read_b128 v[164:167], v163 offset:50176
	ds_read_b128 v[168:171], v163 offset:51200
	ds_read_b128 v[172:175], v163 offset:52224
	ds_read_b128 v[176:179], v163 offset:53248
	ds_read_b128 v[180:183], v163 offset:54272
	ds_read_b128 v[184:187], v163 offset:55296
	ds_read_b128 v[202:205], v163 offset:56320
	global_load_lds_dwordx4 v[158:159], off
	v_lshl_add_u64 v[158:159], v[196:197], 0, s[88:89]
	s_mov_b32 m0, s55
	s_nop 0
	global_load_lds_dwordx4 v[158:159], off
	s_barrier
	s_waitcnt lgkmcnt(0)
	s_setprio 1
	s_waitcnt lgkmcnt(0)
	v_mfma_f32_16x16x32_bf16 v[62:65], v[122:125], v[154:157], v[62:65]
	v_mfma_f32_16x16x32_bf16 v[58:61], v[130:133], v[154:157], v[58:61]
	v_mfma_f32_16x16x32_bf16 v[46:49], v[122:125], v[168:171], v[46:49]
	v_mfma_f32_16x16x32_bf16 v[42:45], v[130:133], v[168:171], v[42:45]
	v_mfma_f32_16x16x32_bf16 v[30:33], v[122:125], v[176:179], v[30:33]
	v_mfma_f32_16x16x32_bf16 v[26:29], v[130:133], v[176:179], v[26:29]
	v_mfma_f32_16x16x32_bf16 v[14:17], v[122:125], v[184:187], v[14:17]
	v_mfma_f32_16x16x32_bf16 v[10:13], v[130:133], v[184:187], v[10:13]
	v_mfma_f32_16x16x32_bf16 v[62:65], v[126:129], v[164:167], v[62:65]
	v_mfma_f32_16x16x32_bf16 v[58:61], v[134:137], v[164:167], v[58:61]
	v_mfma_f32_16x16x32_bf16 v[46:49], v[126:129], v[172:175], v[46:49]
	v_mfma_f32_16x16x32_bf16 v[42:45], v[134:137], v[172:175], v[42:45]
	v_mfma_f32_16x16x32_bf16 v[30:33], v[126:129], v[180:183], v[30:33]
	v_mfma_f32_16x16x32_bf16 v[26:29], v[134:137], v[180:183], v[26:29]
	v_mfma_f32_16x16x32_bf16 v[14:17], v[126:129], v[202:205], v[14:17]
	v_mfma_f32_16x16x32_bf16 v[10:13], v[134:137], v[202:205], v[10:13]
	s_setprio 0
	s_barrier
	s_add_u32 s0, s34, 0x40080
	s_addc_u32 s1, s35, 0
	s_mov_b32 m0, s60
	v_lshl_add_u64 v[122:123], s[0:1], 0, v[148:149]
	global_load_lds_dwordx4 v[122:123], off
	v_lshl_add_u64 v[122:123], s[0:1], 0, v[146:147]
	s_mov_b32 m0, s61
	s_nop 0
	global_load_lds_dwordx4 v[122:123], off
	s_waitcnt vmcnt(6)
	s_barrier
	s_setprio 1
	v_mfma_f32_16x16x32_bf16 v[54:57], v[206:209], v[154:157], v[54:57]
	v_mfma_f32_16x16x32_bf16 v[50:53], v[214:217], v[154:157], v[50:53]
	v_mfma_f32_16x16x32_bf16 v[38:41], v[206:209], v[168:171], v[38:41]
	v_mfma_f32_16x16x32_bf16 v[34:37], v[214:217], v[168:171], v[34:37]
	v_mfma_f32_16x16x32_bf16 v[22:25], v[206:209], v[176:179], v[22:25]
	v_mfma_f32_16x16x32_bf16 v[18:21], v[214:217], v[176:179], v[18:21]
	v_mfma_f32_16x16x32_bf16 v[6:9], v[206:209], v[184:187], v[6:9]
	v_mfma_f32_16x16x32_bf16 v[2:5], v[214:217], v[184:187], v[2:5]
	v_mfma_f32_16x16x32_bf16 v[54:57], v[210:213], v[164:167], v[54:57]
	v_mfma_f32_16x16x32_bf16 v[50:53], v[218:221], v[164:167], v[50:53]
	v_mfma_f32_16x16x32_bf16 v[38:41], v[210:213], v[172:175], v[38:41]
	v_mfma_f32_16x16x32_bf16 v[34:37], v[218:221], v[172:175], v[34:37]
	v_mfma_f32_16x16x32_bf16 v[22:25], v[210:213], v[180:183], v[22:25]
	v_mfma_f32_16x16x32_bf16 v[18:21], v[218:221], v[180:183], v[18:21]
	v_mfma_f32_16x16x32_bf16 v[6:9], v[210:213], v[202:205], v[6:9]
	v_mfma_f32_16x16x32_bf16 v[2:5], v[218:221], v[202:205], v[2:5]
	s_setprio 0
	s_add_i32 s71, s71, 2
	s_add_u32 s20, s20, 0x100
	s_addc_u32 s21, s21, 0
	s_add_u32 s69, s69, 0x100
	s_addc_u32 s70, s70, 0
	s_cmp_gt_u32 s71, 13
	s_barrier
	s_cbranch_scc0 .LBB0_794
	s_lshl_b32 s3, s42, 8
	s_add_i32 s0, s3, 0xfffff000
	s_lshr_b32 s0, s0, 11
	s_mulk_i32 s0, 0x1800
	s_addk_i32 s0, 0x1800
	v_add_u32_e32 v158, s3, v160
	s_cmp_gt_i32 s42, 15
	v_ashrrev_i32_e32 v159, 31, v158
	v_add_u32_e32 v0, 0xfffff000, v158
	v_lshl_or_b32 v194, s66, 8, v162
	s_cselect_b32 s86, s0, 0
	v_lshlrev_b64 v[218:219], 12, v[0:1]
	v_lshlrev_b64 v[220:221], 12, v[158:159]
	s_lshl_b64 s[0:1], s[86:87], 2
	v_ashrrev_i32_e32 v195, 31, v194
	v_lshl_add_u64 v[220:221], s[44:45], 0, v[220:221]
	v_lshl_add_u64 v[218:219], s[46:47], 0, v[218:219]
	v_cmp_gt_i32_e32 vcc, s33, v158
	v_lshlrev_b64 v[196:197], 2, v[194:195]
	s_add_u32 s0, s37, s0
	v_cndmask_b32_e32 v219, v219, v221, vcc
	v_cndmask_b32_e32 v218, v218, v220, vcc
	v_lshl_add_u64 v[154:155], v[218:219], 0, v[196:197]
	s_addc_u32 s1, s38, s1
	v_lshl_add_u64 v[218:219], s[0:1], 0, v[196:197]
	global_load_dwordx4 v[134:137], v[218:219], off
	global_load_dwordx4 v[130:133], v[218:219], off offset:16
	global_load_dwordx4 v[122:125], v[218:219], off offset:528
	global_load_dwordx4 v[126:129], v[218:219], off offset:512
	v_lshlrev_b64 v[196:197], 1, v[194:195]
	v_lshlrev_b64 v[156:157], 11, v[158:159]
	v_lshl_add_u64 v[156:157], s[12:13], 0, v[156:157]
	v_lshl_add_u64 v[156:157], v[156:157], 0, v[196:197]
	s_mov_b32 s66, s2
	s_mov_b64 s[34:35], s[16:17]
	s_mov_b64 s[20:21], s[14:15]
	s_mov_b32 s42, s6
	global_load_dwordx4 v[164:167], v[154:155], off
	global_load_dwordx4 v[168:171], v[154:155], off offset:16
	global_load_dwordx4 v[172:175], v[154:155], off offset:512
	global_load_dwordx4 v[176:179], v[154:155], off offset:528
	s_mov_b32 s0, 0x10000
	s_mov_b32 s1, 0
	v_lshl_add_u64 v[154:155], v[154:155], 0, s[0:1]
	global_load_dwordx4 v[180:183], v[154:155], off
	global_load_dwordx4 v[184:187], v[154:155], off offset:16
	global_load_dwordx4 v[202:205], v[154:155], off offset:512
	global_load_dwordx4 v[206:209], v[154:155], off offset:528
	v_lshl_add_u64 v[154:155], v[154:155], 0, s[0:1]
	global_load_dwordx4 v[210:213], v[154:155], off
	global_load_dwordx4 v[214:217], v[154:155], off offset:16
	global_load_dwordx4 v[194:197], v[154:155], off offset:512
	global_load_dwordx4 v[218:221], v[154:155], off offset:528
	v_lshl_add_u64 v[154:155], v[154:155], 0, s[0:1]
	s_waitcnt vmcnt(10)
	v_pk_mul_f32 v[166:167], v[166:167], s[56:57] op_sel_hi:[1,0]
	v_pk_mul_f32 v[164:165], v[164:165], s[56:57] op_sel_hi:[1,0]
	v_pk_mul_f32 v[170:171], v[170:171], s[56:57] op_sel_hi:[1,0]
	v_pk_mul_f32 v[168:169], v[168:169], s[56:57] op_sel_hi:[1,0]
	v_pk_fma_f32 v[144:145], v[144:145], v[136:137], v[166:167]
	v_pk_fma_f32 v[142:143], v[142:143], v[134:135], v[164:165]
	v_pk_fma_f32 v[140:141], v[140:141], v[132:133], v[170:171]
	v_pk_fma_f32 v[138:139], v[138:139], v[130:131], v[168:169]
	v_cvt_pk_bf16_f32 v164, v142, v143
	v_cvt_pk_bf16_f32 v165, v144, v145
	v_cvt_pk_bf16_f32 v166, v138, v139
	v_cvt_pk_bf16_f32 v167, v140, v141
	global_store_dwordx4 v[156:157], v[164:167], off
	s_nop 0
	global_load_dwordx4 v[164:167], v[154:155], off
	global_load_dwordx4 v[168:171], v[154:155], off offset:16
	s_waitcnt vmcnt(11)
	v_pk_mul_f32 v[174:175], v[174:175], s[56:57] op_sel_hi:[1,0]
	v_pk_mul_f32 v[172:173], v[172:173], s[56:57] op_sel_hi:[1,0]
	v_pk_mul_f32 v[178:179], v[178:179], s[56:57] op_sel_hi:[1,0]
	v_pk_mul_f32 v[176:177], v[176:177], s[56:57] op_sel_hi:[1,0]
	v_pk_fma_f32 v[120:121], v[120:121], v[128:129], v[174:175]
	v_pk_fma_f32 v[118:119], v[118:119], v[126:127], v[172:173]
	v_pk_fma_f32 v[116:117], v[116:117], v[124:125], v[178:179]
	v_pk_fma_f32 v[114:115], v[114:115], v[122:123], v[176:177]
	v_cvt_pk_bf16_f32 v172, v118, v119
	v_cvt_pk_bf16_f32 v173, v120, v121
	v_cvt_pk_bf16_f32 v174, v114, v115
	v_cvt_pk_bf16_f32 v175, v116, v117
	global_store_dwordx4 v[156:157], v[172:175], off offset:256
	s_mov_b32 s0, 0x8000
	v_lshl_add_u64 v[156:157], v[156:157], 0, s[0:1]
	global_load_dwordx4 v[172:175], v[154:155], off offset:512
	global_load_dwordx4 v[176:179], v[154:155], off offset:528
	s_mov_b32 s0, 0x50000
	v_lshl_add_u64 v[154:155], v[154:155], 0, s[0:1]
	s_waitcnt vmcnt(12)
	v_pk_mul_f32 v[182:183], v[182:183], s[56:57] op_sel_hi:[1,0]
	v_pk_mul_f32 v[180:181], v[180:181], s[56:57] op_sel_hi:[1,0]
	v_pk_mul_f32 v[186:187], v[186:187], s[56:57] op_sel_hi:[1,0]
	v_pk_mul_f32 v[184:185], v[184:185], s[56:57] op_sel_hi:[1,0]
	v_pk_fma_f32 v[112:113], v[112:113], v[136:137], v[182:183]
	v_pk_fma_f32 v[110:111], v[110:111], v[134:135], v[180:181]
	v_pk_fma_f32 v[108:109], v[108:109], v[132:133], v[186:187]
	v_pk_fma_f32 v[106:107], v[106:107], v[130:131], v[184:185]
	v_cvt_pk_bf16_f32 v180, v110, v111
	v_cvt_pk_bf16_f32 v181, v112, v113
	v_cvt_pk_bf16_f32 v182, v106, v107
	v_cvt_pk_bf16_f32 v183, v108, v109
	global_store_dwordx4 v[156:157], v[180:183], off
	s_nop 0
	global_load_dwordx4 v[180:183], v[154:155], off
	global_load_dwordx4 v[184:187], v[154:155], off offset:16
	s_waitcnt vmcnt(13)
	v_pk_mul_f32 v[204:205], v[204:205], s[56:57] op_sel_hi:[1,0]
	v_pk_mul_f32 v[202:203], v[202:203], s[56:57] op_sel_hi:[1,0]
	v_pk_mul_f32 v[208:209], v[208:209], s[56:57] op_sel_hi:[1,0]
	v_pk_mul_f32 v[206:207], v[206:207], s[56:57] op_sel_hi:[1,0]
	v_pk_fma_f32 v[104:105], v[104:105], v[128:129], v[204:205]
	v_pk_fma_f32 v[102:103], v[102:103], v[126:127], v[202:203]
	v_pk_fma_f32 v[100:101], v[100:101], v[124:125], v[208:209]
	v_pk_fma_f32 v[98:99], v[98:99], v[122:123], v[206:207]
	v_cvt_pk_bf16_f32 v202, v102, v103
	v_cvt_pk_bf16_f32 v203, v104, v105
	v_cvt_pk_bf16_f32 v204, v98, v99
	v_cvt_pk_bf16_f32 v205, v100, v101
	global_store_dwordx4 v[156:157], v[202:205], off offset:256
	s_mov_b32 s0, 0x8000
	v_lshl_add_u64 v[156:157], v[156:157], 0, s[0:1]
	global_load_dwordx4 v[202:205], v[154:155], off offset:512
	global_load_dwordx4 v[206:209], v[154:155], off offset:528
	s_mov_b32 s0, 0x10000
	v_lshl_add_u64 v[154:155], v[154:155], 0, s[0:1]
	s_waitcnt vmcnt(14)
	v_pk_mul_f32 v[212:213], v[212:213], s[56:57] op_sel_hi:[1,0]
	v_pk_mul_f32 v[210:211], v[210:211], s[56:57] op_sel_hi:[1,0]
	v_pk_mul_f32 v[216:217], v[216:217], s[56:57] op_sel_hi:[1,0]
	v_pk_mul_f32 v[214:215], v[214:215], s[56:57] op_sel_hi:[1,0]
	v_pk_fma_f32 v[96:97], v[96:97], v[136:137], v[212:213]
	v_pk_fma_f32 v[94:95], v[94:95], v[134:135], v[210:211]
	v_pk_fma_f32 v[92:93], v[92:93], v[132:133], v[216:217]
	v_pk_fma_f32 v[90:91], v[90:91], v[130:131], v[214:215]
	v_cvt_pk_bf16_f32 v210, v94, v95
	v_cvt_pk_bf16_f32 v211, v96, v97
	v_cvt_pk_bf16_f32 v212, v90, v91
	v_cvt_pk_bf16_f32 v213, v92, v93
	global_store_dwordx4 v[156:157], v[210:213], off
	s_nop 0
	global_load_dwordx4 v[210:213], v[154:155], off
	global_load_dwordx4 v[214:217], v[154:155], off offset:16
	s_waitcnt vmcnt(15)
	v_pk_mul_f32 v[196:197], v[196:197], s[56:57] op_sel_hi:[1,0]
	v_pk_mul_f32 v[194:195], v[194:195], s[56:57] op_sel_hi:[1,0]
	v_pk_mul_f32 v[220:221], v[220:221], s[56:57] op_sel_hi:[1,0]
	v_pk_mul_f32 v[218:219], v[218:219], s[56:57] op_sel_hi:[1,0]
	v_pk_fma_f32 v[88:89], v[88:89], v[128:129], v[196:197]
	v_pk_fma_f32 v[86:87], v[86:87], v[126:127], v[194:195]
	v_pk_fma_f32 v[84:85], v[84:85], v[124:125], v[220:221]
	v_pk_fma_f32 v[82:83], v[82:83], v[122:123], v[218:219]
	v_cvt_pk_bf16_f32 v194, v86, v87
	v_cvt_pk_bf16_f32 v195, v88, v89
	v_cvt_pk_bf16_f32 v196, v82, v83
	v_cvt_pk_bf16_f32 v197, v84, v85
	global_store_dwordx4 v[156:157], v[194:197], off offset:256
	s_mov_b32 s0, 0x8000
	v_lshl_add_u64 v[156:157], v[156:157], 0, s[0:1]
	global_load_dwordx4 v[194:197], v[154:155], off offset:512
	global_load_dwordx4 v[218:221], v[154:155], off offset:528
	s_mov_b32 s0, 0x10000
	v_lshl_add_u64 v[154:155], v[154:155], 0, s[0:1]
	s_waitcnt vmcnt(15)
	v_pk_mul_f32 v[166:167], v[166:167], s[56:57] op_sel_hi:[1,0]
	v_pk_mul_f32 v[164:165], v[164:165], s[56:57] op_sel_hi:[1,0]
	v_pk_mul_f32 v[170:171], v[170:171], s[56:57] op_sel_hi:[1,0]
	v_pk_mul_f32 v[168:169], v[168:169], s[56:57] op_sel_hi:[1,0]
	v_pk_fma_f32 v[80:81], v[80:81], v[136:137], v[166:167]
	v_pk_fma_f32 v[78:79], v[78:79], v[134:135], v[164:165]
	v_pk_fma_f32 v[76:77], v[76:77], v[132:133], v[170:171]
	v_pk_fma_f32 v[74:75], v[74:75], v[130:131], v[168:169]
	v_cvt_pk_bf16_f32 v164, v78, v79
	v_cvt_pk_bf16_f32 v165, v80, v81
	v_cvt_pk_bf16_f32 v166, v74, v75
	v_cvt_pk_bf16_f32 v167, v76, v77
	global_store_dwordx4 v[156:157], v[164:167], off
	s_nop 0
	global_load_dwordx4 v[164:167], v[154:155], off
	global_load_dwordx4 v[168:171], v[154:155], off offset:16
	s_waitcnt vmcnt(15)
	v_pk_mul_f32 v[174:175], v[174:175], s[56:57] op_sel_hi:[1,0]
	v_pk_mul_f32 v[172:173], v[172:173], s[56:57] op_sel_hi:[1,0]
	v_pk_mul_f32 v[178:179], v[178:179], s[56:57] op_sel_hi:[1,0]
	v_pk_mul_f32 v[176:177], v[176:177], s[56:57] op_sel_hi:[1,0]
	v_pk_fma_f32 v[72:73], v[72:73], v[128:129], v[174:175]
	v_pk_fma_f32 v[70:71], v[70:71], v[126:127], v[172:173]
	v_pk_fma_f32 v[68:69], v[68:69], v[124:125], v[178:179]
	v_pk_fma_f32 v[66:67], v[66:67], v[122:123], v[176:177]
	v_cvt_pk_bf16_f32 v172, v70, v71
	v_cvt_pk_bf16_f32 v173, v72, v73
	v_cvt_pk_bf16_f32 v174, v66, v67
	v_cvt_pk_bf16_f32 v175, v68, v69
	global_store_dwordx4 v[156:157], v[172:175], off offset:256
	s_mov_b32 s0, 0x28000
	v_lshl_add_u64 v[156:157], v[156:157], 0, s[0:1]
	global_load_dwordx4 v[172:175], v[154:155], off offset:512
	global_load_dwordx4 v[176:179], v[154:155], off offset:528
	s_mov_b32 s0, 0x10000
	v_lshl_add_u64 v[154:155], v[154:155], 0, s[0:1]
	s_waitcnt vmcnt(15)
	v_pk_mul_f32 v[182:183], v[182:183], s[56:57] op_sel_hi:[1,0]
	v_pk_mul_f32 v[180:181], v[180:181], s[56:57] op_sel_hi:[1,0]
	v_pk_mul_f32 v[186:187], v[186:187], s[56:57] op_sel_hi:[1,0]
	v_pk_mul_f32 v[184:185], v[184:185], s[56:57] op_sel_hi:[1,0]
	v_pk_fma_f32 v[64:65], v[64:65], v[136:137], v[182:183]
	v_pk_fma_f32 v[62:63], v[62:63], v[134:135], v[180:181]
	v_pk_fma_f32 v[60:61], v[60:61], v[132:133], v[186:187]
	v_pk_fma_f32 v[58:59], v[58:59], v[130:131], v[184:185]
	v_cvt_pk_bf16_f32 v180, v62, v63
	v_cvt_pk_bf16_f32 v181, v64, v65
	v_cvt_pk_bf16_f32 v182, v58, v59
	v_cvt_pk_bf16_f32 v183, v60, v61
	global_store_dwordx4 v[156:157], v[180:183], off
	s_nop 0
	global_load_dwordx4 v[180:183], v[154:155], off
	global_load_dwordx4 v[184:187], v[154:155], off offset:16
	s_waitcnt vmcnt(15)
	v_pk_mul_f32 v[204:205], v[204:205], s[56:57] op_sel_hi:[1,0]
	v_pk_mul_f32 v[202:203], v[202:203], s[56:57] op_sel_hi:[1,0]
	v_pk_mul_f32 v[208:209], v[208:209], s[56:57] op_sel_hi:[1,0]
	v_pk_mul_f32 v[206:207], v[206:207], s[56:57] op_sel_hi:[1,0]
	v_pk_fma_f32 v[56:57], v[56:57], v[128:129], v[204:205]
	v_pk_fma_f32 v[54:55], v[54:55], v[126:127], v[202:203]
	v_pk_fma_f32 v[52:53], v[52:53], v[124:125], v[208:209]
	v_pk_fma_f32 v[50:51], v[50:51], v[122:123], v[206:207]
	v_cvt_pk_bf16_f32 v202, v54, v55
	v_cvt_pk_bf16_f32 v203, v56, v57
	v_cvt_pk_bf16_f32 v204, v50, v51
	v_cvt_pk_bf16_f32 v205, v52, v53
	global_store_dwordx4 v[156:157], v[202:205], off offset:256
	s_mov_b32 s0, 0x8000
	v_lshl_add_u64 v[156:157], v[156:157], 0, s[0:1]
	global_load_dwordx4 v[202:205], v[154:155], off offset:512
	global_load_dwordx4 v[206:209], v[154:155], off offset:528
	s_waitcnt vmcnt(15)
	v_pk_mul_f32 v[212:213], v[212:213], s[56:57] op_sel_hi:[1,0]
	v_pk_mul_f32 v[210:211], v[210:211], s[56:57] op_sel_hi:[1,0]
	v_pk_mul_f32 v[216:217], v[216:217], s[56:57] op_sel_hi:[1,0]
	v_pk_mul_f32 v[214:215], v[214:215], s[56:57] op_sel_hi:[1,0]
	v_pk_fma_f32 v[48:49], v[48:49], v[136:137], v[212:213]
	v_pk_fma_f32 v[46:47], v[46:47], v[134:135], v[210:211]
	v_pk_fma_f32 v[44:45], v[44:45], v[132:133], v[216:217]
	v_pk_fma_f32 v[42:43], v[42:43], v[130:131], v[214:215]
	v_cvt_pk_bf16_f32 v210, v46, v47
	v_cvt_pk_bf16_f32 v211, v48, v49
	v_cvt_pk_bf16_f32 v212, v42, v43
	v_cvt_pk_bf16_f32 v213, v44, v45
	global_store_dwordx4 v[156:157], v[210:213], off
	s_nop 0
	s_waitcnt vmcnt(13)
	v_pk_mul_f32 v[196:197], v[196:197], s[56:57] op_sel_hi:[1,0]
	v_pk_mul_f32 v[194:195], v[194:195], s[56:57] op_sel_hi:[1,0]
	v_pk_mul_f32 v[220:221], v[220:221], s[56:57] op_sel_hi:[1,0]
	v_pk_mul_f32 v[218:219], v[218:219], s[56:57] op_sel_hi:[1,0]
	v_pk_fma_f32 v[40:41], v[40:41], v[128:129], v[196:197]
	v_pk_fma_f32 v[38:39], v[38:39], v[126:127], v[194:195]
	v_pk_fma_f32 v[36:37], v[36:37], v[124:125], v[220:221]
	v_pk_fma_f32 v[34:35], v[34:35], v[122:123], v[218:219]
	v_cvt_pk_bf16_f32 v194, v38, v39
	v_cvt_pk_bf16_f32 v195, v40, v41
	v_cvt_pk_bf16_f32 v196, v34, v35
	v_cvt_pk_bf16_f32 v197, v36, v37
	global_store_dwordx4 v[156:157], v[194:197], off offset:256
	v_lshl_add_u64 v[156:157], v[156:157], 0, s[0:1]
	s_waitcnt vmcnt(11)
	v_pk_mul_f32 v[166:167], v[166:167], s[56:57] op_sel_hi:[1,0]
	v_pk_mul_f32 v[164:165], v[164:165], s[56:57] op_sel_hi:[1,0]
	v_pk_mul_f32 v[170:171], v[170:171], s[56:57] op_sel_hi:[1,0]
	v_pk_mul_f32 v[168:169], v[168:169], s[56:57] op_sel_hi:[1,0]
	v_pk_fma_f32 v[32:33], v[32:33], v[136:137], v[166:167]
	v_pk_fma_f32 v[30:31], v[30:31], v[134:135], v[164:165]
	v_pk_fma_f32 v[28:29], v[28:29], v[132:133], v[170:171]
	v_pk_fma_f32 v[26:27], v[26:27], v[130:131], v[168:169]
	v_cvt_pk_bf16_f32 v164, v30, v31
	v_cvt_pk_bf16_f32 v165, v32, v33
	v_cvt_pk_bf16_f32 v166, v26, v27
	v_cvt_pk_bf16_f32 v167, v28, v29
	global_store_dwordx4 v[156:157], v[164:167], off
	s_nop 0
	s_waitcnt vmcnt(9)
	v_pk_mul_f32 v[174:175], v[174:175], s[56:57] op_sel_hi:[1,0]
	v_pk_mul_f32 v[172:173], v[172:173], s[56:57] op_sel_hi:[1,0]
	v_pk_mul_f32 v[178:179], v[178:179], s[56:57] op_sel_hi:[1,0]
	v_pk_mul_f32 v[176:177], v[176:177], s[56:57] op_sel_hi:[1,0]
	v_pk_fma_f32 v[24:25], v[24:25], v[128:129], v[174:175]
	v_pk_fma_f32 v[22:23], v[22:23], v[126:127], v[172:173]
	v_pk_fma_f32 v[20:21], v[20:21], v[124:125], v[178:179]
	v_pk_fma_f32 v[18:19], v[18:19], v[122:123], v[176:177]
	v_cvt_pk_bf16_f32 v172, v22, v23
	v_cvt_pk_bf16_f32 v173, v24, v25
	v_cvt_pk_bf16_f32 v174, v18, v19
	v_cvt_pk_bf16_f32 v175, v20, v21
	global_store_dwordx4 v[156:157], v[172:175], off offset:256
	v_lshl_add_u64 v[156:157], v[156:157], 0, s[0:1]
	s_waitcnt vmcnt(7)
	v_pk_mul_f32 v[182:183], v[182:183], s[56:57] op_sel_hi:[1,0]
	v_pk_mul_f32 v[180:181], v[180:181], s[56:57] op_sel_hi:[1,0]
	v_pk_mul_f32 v[186:187], v[186:187], s[56:57] op_sel_hi:[1,0]
	v_pk_mul_f32 v[184:185], v[184:185], s[56:57] op_sel_hi:[1,0]
	v_pk_fma_f32 v[16:17], v[16:17], v[136:137], v[182:183]
	v_pk_fma_f32 v[14:15], v[14:15], v[134:135], v[180:181]
	v_pk_fma_f32 v[12:13], v[12:13], v[132:133], v[186:187]
	v_pk_fma_f32 v[10:11], v[10:11], v[130:131], v[184:185]
	v_cvt_pk_bf16_f32 v180, v14, v15
	v_cvt_pk_bf16_f32 v181, v16, v17
	v_cvt_pk_bf16_f32 v182, v10, v11
	v_cvt_pk_bf16_f32 v183, v12, v13
	global_store_dwordx4 v[156:157], v[180:183], off
	s_nop 0
	s_waitcnt vmcnt(5)
	v_pk_mul_f32 v[204:205], v[204:205], s[56:57] op_sel_hi:[1,0]
	v_pk_mul_f32 v[202:203], v[202:203], s[56:57] op_sel_hi:[1,0]
	v_pk_mul_f32 v[208:209], v[208:209], s[56:57] op_sel_hi:[1,0]
	v_pk_mul_f32 v[206:207], v[206:207], s[56:57] op_sel_hi:[1,0]
	v_pk_fma_f32 v[8:9], v[8:9], v[128:129], v[204:205]
	v_pk_fma_f32 v[6:7], v[6:7], v[126:127], v[202:203]
	v_pk_fma_f32 v[4:5], v[4:5], v[124:125], v[208:209]
	v_pk_fma_f32 v[2:3], v[2:3], v[122:123], v[206:207]
	v_cvt_pk_bf16_f32 v202, v6, v7
	v_cvt_pk_bf16_f32 v203, v8, v9
	v_cvt_pk_bf16_f32 v204, v2, v3
	v_cvt_pk_bf16_f32 v205, v4, v5
	global_store_dwordx4 v[156:157], v[202:205], off offset:256
	s_nop 0
	s_and_b64 vcc, exec, s[40:41]
	s_cbranch_vccz .LBB0_791
	s_waitcnt vmcnt(0)
	v_readlane_b32 s48, v254, 11
	s_cmpk_gt_u32 s4, 0xff
	v_readlane_b32 s49, v254, 12
	v_readlane_b32 s50, v254, 13
	s_mov_b32 s58, 0x800000
	s_mov_b32 s37, s75
	v_readlane_b32 s51, v254, 14
	s_cbranch_scc1 .LBB0_798
	s_barrier
